# v67 + P0 memory-token rows: four loads in flight + P4 dec_out epilogue: both residual loads issued early, store drain removed
# speedup vs baseline: 1.0126x; 1.0126x over previous
.LBB0_53:
	global_load_dwordx4 v[8:11], v[6:7], off offset:-3072
	global_load_dwordx4 v[12:15], v[6:7], off offset:-2048
	global_load_dwordx4 v[16:19], v[6:7], off offset:-1024
	global_load_dwordx4 v[20:23], v[6:7], off
	s_add_i32 s4, s4, s24
	s_cmpk_gt_i32 s4, 0x7ff
	v_lshl_add_u64 v[6:7], v[6:7], 0, s[2:3]
	s_waitcnt vmcnt(3)
	v_cvt_pk_bf16_f32 v8, v8, v9
	v_cvt_pk_bf16_f32 v9, v10, v11
	global_store_dwordx2 v[4:5], v[8:9], off
	s_waitcnt vmcnt(3)
	v_cvt_pk_bf16_f32 v12, v12, v13
	v_cvt_pk_bf16_f32 v13, v14, v15
	global_store_dwordx2 v[4:5], v[12:13], off offset:512
	s_waitcnt vmcnt(3)
	v_cvt_pk_bf16_f32 v16, v16, v17
	v_cvt_pk_bf16_f32 v17, v18, v19
	global_store_dwordx2 v[4:5], v[16:17], off offset:1024
	s_waitcnt vmcnt(3)
	v_cvt_pk_bf16_f32 v20, v20, v21
	v_cvt_pk_bf16_f32 v21, v22, v23
	global_store_dwordx2 v[4:5], v[20:21], off offset:1536
	v_lshl_add_u64 v[4:5], v[4:5], 0, s[0:1]
	s_cbranch_scc0 .LBB0_53

.LBB0_1031:
	s_cmp_lt_i32 s4, 5
	s_cselect_b64 s[0:1], -1, 0
	s_cmp_gt_i32 s5, 4
	s_cselect_b64 s[2:3], -1, 0
	s_and_b64 s[0:1], s[0:1], s[2:3]
	s_andn2_b64 vcc, exec, s[0:1]
	s_cbranch_vccnz .LBB0_1155
	v_mov_b32_e32 v1, v0
	s_cmpk_gt_i32 s92, 0x7f
	v_readfirstlane_b32 s0, v1
	s_cbranch_scc1 .LBB0_1034
	s_and_b32 s4, s92, 0xffffffe0
	s_ashr_i32 s0, s0, 6
	s_and_b32 s1, s92, 31
	s_ashr_i32 s2, s4, 31
	s_add_u32 s3, s4, 0x4000
	s_waitcnt vmcnt(0)
	v_and_b32_e32 v54, 31, v1
	s_addc_u32 s2, s2, 0
	v_or_b32_e32 v2, s3, v54
	v_mov_b32_e32 v3, s2
	s_lshl_b32 s2, s0, 8
	v_lshlrev_b64 v[2:3], 12, v[2:3]
	s_ashr_i32 s3, s2, 31
	s_lshl_b32 s5, s1, 17
	v_bfe_u32 v55, v1, 5, 1
	v_lshl_or_b32 v4, v54, 12, s5
	v_mov_b32_e32 v5, 0
	s_lshl_b64 s[2:3], s[2:3], 1
	v_lshl_add_u64 v[2:3], s[96:97], 0, v[2:3]
	v_lshl_add_u64 v[6:7], s[96:97], 0, v[4:5]
	v_lshl_add_u64 v[2:3], v[2:3], 0, s[2:3]
	v_lshlrev_b32_e32 v4, 4, v55
	v_lshl_add_u64 v[6:7], v[6:7], 0, s[2:3]
	v_lshl_add_u64 v[10:11], v[2:3], 0, v[4:5]
	s_mov_b32 s2, 0x1b000000
	v_add_co_u32_e32 v2, vcc, s2, v10
	v_lshl_add_u64 v[12:13], v[6:7], 0, v[4:5]
	s_nop 0
	v_addc_co_u32_e32 v3, vcc, 0, v11, vcc
	global_load_dwordx4 v[56:59], v[2:3], off
	s_mov_b32 s2, 0x1400000
	v_add_co_u32_e32 v6, vcc, s2, v12
	s_mov_b64 s[2:3], 0x1b000000
	s_nop 0
	v_addc_co_u32_e32 v7, vcc, 0, v13, vcc
	global_load_dwordx4 v[60:63], v[6:7], off
	v_lshl_add_u64 v[50:51], v[10:11], 0, s[2:3]
	global_load_dwordx4 v[64:67], v[50:51], off offset:32
	s_mov_b64 s[2:3], 0x1400000
	v_lshl_add_u64 v[52:53], v[12:13], 0, s[2:3]
	global_load_dwordx4 v[68:71], v[52:53], off offset:32
	global_load_dwordx4 v[72:75], v[50:51], off offset:64
	global_load_dwordx4 v[76:79], v[52:53], off offset:64
	global_load_dwordx4 v[80:83], v[50:51], off offset:96
	global_load_dwordx4 v[84:87], v[52:53], off offset:96
	global_load_dwordx4 v[88:91], v[50:51], off offset:128
	global_load_dwordx4 v[92:95], v[50:51], off offset:480
	global_load_dwordx4 v[96:99], v[52:53], off offset:128
	global_load_dwordx4 v[100:103], v[50:51], off offset:160
	global_load_dwordx4 v[104:107], v[52:53], off offset:160
	global_load_dwordx4 v[108:111], v[50:51], off offset:192
	global_load_dwordx4 v[112:115], v[52:53], off offset:192
	global_load_dwordx4 v[116:119], v[50:51], off offset:224
	global_load_dwordx4 v[120:123], v[52:53], off offset:224
	global_load_dwordx4 v[124:127], v[50:51], off offset:256
	global_load_dwordx4 v[128:131], v[52:53], off offset:256
	global_load_dwordx4 v[132:135], v[50:51], off offset:288
	global_load_dwordx4 v[136:139], v[52:53], off offset:288
	global_load_dwordx4 v[140:143], v[50:51], off offset:320
	global_load_dwordx4 v[144:147], v[52:53], off offset:320
	global_load_dwordx4 v[148:151], v[50:51], off offset:352
	global_load_dwordx4 v[152:155], v[52:53], off offset:352
	global_load_dwordx4 v[156:159], v[50:51], off offset:384
	global_load_dwordx4 v[160:163], v[52:53], off offset:384
	global_load_dwordx4 v[164:167], v[50:51], off offset:416
	global_load_dwordx4 v[168:171], v[52:53], off offset:416
	global_load_dwordx4 v[172:175], v[50:51], off offset:448
	global_load_dwordx4 v[176:179], v[52:53], off offset:448
	global_load_dwordx4 v[180:183], v[52:53], off offset:480
	v_and_b32_e32 v1, 63, v1
	v_lshlrev_b32_e32 v1, 2, v1
	s_waitcnt vmcnt(30)
	v_mfma_f32_32x32x16_bf16 v[2:17], v[56:59], v[60:63], 0
	s_waitcnt vmcnt(28)
	v_mfma_f32_32x32x16_bf16 v[2:17], v[64:67], v[68:71], v[2:17]
	s_waitcnt vmcnt(26)
	v_mfma_f32_32x32x16_bf16 v[2:17], v[72:75], v[76:79], v[2:17]
	s_waitcnt vmcnt(24)
	v_mfma_f32_32x32x16_bf16 v[2:17], v[80:83], v[84:87], v[2:17]
	s_waitcnt vmcnt(21)
	v_mfma_f32_32x32x16_bf16 v[2:17], v[88:91], v[96:99], v[2:17]
	s_waitcnt vmcnt(19)
	v_mfma_f32_32x32x16_bf16 v[2:17], v[100:103], v[104:107], v[2:17]
	s_waitcnt vmcnt(17)
	v_mfma_f32_32x32x16_bf16 v[2:17], v[108:111], v[112:115], v[2:17]
	s_waitcnt vmcnt(15)
	v_mfma_f32_32x32x16_bf16 v[2:17], v[116:119], v[120:123], v[2:17]
	s_waitcnt vmcnt(13)
	v_mfma_f32_32x32x16_bf16 v[2:17], v[124:127], v[128:131], v[2:17]
	s_waitcnt vmcnt(11)
	v_mfma_f32_32x32x16_bf16 v[2:17], v[132:135], v[136:139], v[2:17]
	s_waitcnt vmcnt(9)
	v_mfma_f32_32x32x16_bf16 v[2:17], v[140:143], v[144:147], v[2:17]
	s_waitcnt vmcnt(7)
	v_mfma_f32_32x32x16_bf16 v[2:17], v[148:151], v[152:155], v[2:17]
	v_lshlrev_b32_e32 v39, 2, v54
	v_lshl_or_b32 v39, s1, 7, v39
	s_lshl_b32 s1, s0, 12
	s_add_i32 s1, s1, 0
	s_add_u32 s2, s96, 0x23b00000
	v_lshl_or_b32 v38, v55, 2, s4
	s_waitcnt vmcnt(5)
	v_mfma_f32_32x32x16_bf16 v[2:17], v[156:159], v[160:163], v[2:17]
	s_addc_u32 s3, s97, 0
	s_lshl_b32 s4, s0, 2
	s_and_b32 s4, s4, -8
	s_waitcnt vmcnt(3)
	v_mfma_f32_32x32x16_bf16 v[2:17], v[164:167], v[168:171], v[2:17]
	v_add_u32_e32 v30, s1, v1
	s_lshl_b32 s1, s0, 1
	v_add_u32_e32 v1, 0, v1
	s_waitcnt vmcnt(1)
	v_mfma_f32_32x32x16_bf16 v[2:17], v[172:175], v[176:179], v[2:17]
	v_add_u32_e32 v22, s4, v38
	v_and_or_b32 v18, s1, 2, v22
	v_ashrrev_i32_e32 v19, 31, v18
	v_lshlrev_b64 v[18:19], 12, v[18:19]
	v_or_b32_e32 v18, v18, v39
	v_lshl_add_u64 v[20:21], s[70:71], 0, v[18:19]
	global_load_dword v184, v[20:21], off
	s_waitcnt vmcnt(1)
	v_mfma_f32_32x32x16_bf16 v[2:17], v[92:95], v[180:183], v[2:17]
	s_nop 11
	ds_write2st64_b32 v30, v2, v3 offset1:1
	ds_write2st64_b32 v30, v4, v5 offset0:2 offset1:3
	ds_write2st64_b32 v30, v6, v7 offset0:4 offset1:5
	ds_write2st64_b32 v30, v8, v9 offset0:6 offset1:7
	ds_write2st64_b32 v30, v10, v11 offset0:8 offset1:9
	ds_write2st64_b32 v30, v12, v13 offset0:10 offset1:11
	ds_write2st64_b32 v30, v14, v15 offset0:12 offset1:13
	ds_write2st64_b32 v30, v16, v17 offset0:14 offset1:15
	s_waitcnt lgkmcnt(0)
	s_barrier
	v_lshl_add_u32 v14, s0, 9, v1
	ds_read2st64_b32 v[6:7], v14 offset1:16
	ds_read2st64_b32 v[10:11], v14 offset0:32 offset1:48
	ds_read2st64_b32 v[12:13], v14 offset0:64 offset1:80
	ds_read2st64_b32 v[14:15], v14 offset0:96 offset1:112
	s_or_b32 s0, s1, 1
	v_and_or_b32 v2, s0, 3, v22
	v_ashrrev_i32_e32 v3, 31, v2
	s_waitcnt lgkmcnt(3)
	v_add_f32_e32 v6, 0, v6
	v_add_f32_e32 v6, v6, v7
	s_waitcnt lgkmcnt(2)
	v_add_f32_e32 v6, v6, v10
	v_add_f32_e32 v6, v6, v11
	s_waitcnt lgkmcnt(1)
	v_add_f32_e32 v6, v6, v12
	v_add_f32_e32 v6, v6, v13
	s_waitcnt lgkmcnt(0)
	v_add_f32_e32 v6, v6, v14
	v_lshlrev_b64 v[2:3], 12, v[2:3]
	v_add_f32_e32 v6, v6, v15
	v_or_b32_e32 v2, v2, v39
	v_lshl_add_u64 v[4:5], s[2:3], 0, v[18:19]
	v_lshl_add_u64 v[8:9], s[70:71], 0, v[2:3]
	global_load_dword v12, v[8:9], off
	v_lshl_add_u32 v1, s0, 8, v1
	v_lshl_add_u64 v[2:3], s[2:3], 0, v[2:3]
	s_waitcnt vmcnt(0)
	v_fmac_f32_e32 v6, 0x3f9837f0, v184
	global_store_dword v[4:5], v6, off
	ds_read2st64_b32 v[4:5], v1 offset1:16
	ds_read2st64_b32 v[6:7], v1 offset0:32 offset1:48
	ds_read2st64_b32 v[8:9], v1 offset0:64 offset1:80
	ds_read2st64_b32 v[10:11], v1 offset0:96 offset1:112
	s_waitcnt lgkmcnt(3)
	v_add_f32_e32 v1, 0, v4
	v_add_f32_e32 v1, v1, v5
	s_waitcnt lgkmcnt(2)
	v_add_f32_e32 v1, v1, v6
	v_add_f32_e32 v1, v1, v7
	s_waitcnt lgkmcnt(1)
	v_add_f32_e32 v1, v1, v8
	v_add_f32_e32 v1, v1, v9
	s_waitcnt lgkmcnt(0)
	v_add_f32_e32 v1, v1, v10
	v_add_f32_e32 v1, v1, v11
	v_fmac_f32_e32 v1, 0x3f9837f0, v12
	global_store_dword v[2:3], v1, off
